# seam L1-invalidate hoisted before spin (7 local/group seams) + P7 epilogue residual loads all issued before first wait
# baseline (speedup 1.0000x reference)
.LBB0_416:
	v_cmp_eq_u32_e32 vcc, 0, v1
	s_mov_b64 s[40:41], -1
	s_mov_b64 s[6:7], -1
	s_cbranch_vccnz .LBB0_445
	s_waitcnt vmcnt(0)
	v_mov_b32_e32 v2, 0
	s_barrier
	s_mov_b64 s[6:7], exec
	v_readlane_b32 s4, v254, 2
	v_readlane_b32 s5, v254, 3
	s_and_b64 s[4:5], s[6:7], s[4:5]
	s_mov_b64 exec, s[4:5]
	s_cbranch_execz .LBB0_421
	s_mov_b64 s[10:11], exec
	v_mbcnt_lo_u32_b32 v0, s10, 0
	v_mbcnt_hi_u32_b32 v0, s11, v0
	v_cmp_eq_u32_e32 vcc, 0, v0
	s_waitcnt vmcnt(0) expcnt(0) lgkmcnt(0)
	s_and_saveexec_b64 s[8:9], vcc
	s_cbranch_execz .LBB0_420
	v_readlane_b32 s3, v254, 6
	s_lshl_b32 s3, s3, 6
	s_add_u32 s4, s0, s3
	s_addc_u32 s5, s1, 0
	s_bcnt1_i32_b64 s3, s[10:11]
	v_mov_b32_e32 v1, 0x6000
	v_mov_b32_e32 v2, s3
	global_atomic_add v1, v1, v2, s[4:5] offset:1024 sc0
	buffer_inv sc1
.LBB0_420:
	s_or_b64 exec, exec, s[8:9]
	s_waitcnt vmcnt(1)
	v_readfirstlane_b32 s3, v1
	s_nop 1
	v_add_u32_e32 v2, s3, v0

.LBB0_443:
	s_or_b64 exec, exec, s[8:9]
	s_waitcnt vmcnt(0) lgkmcnt(0)
	s_waitcnt vmcnt(0)

.LBB0_613:
	s_and_b64 vcc, exec, s[10:11]
	s_cbranch_vccz .LBB0_635
	s_waitcnt vmcnt(0)
	v_mov_b32_e32 v2, 0
	s_waitcnt lgkmcnt(0)
	s_barrier
	s_mov_b64 s[10:11], exec
	v_readlane_b32 s4, v254, 2
	v_readlane_b32 s5, v254, 3
	s_and_b64 s[4:5], s[10:11], s[4:5]
	s_mov_b64 exec, s[4:5]
	s_cbranch_execz .LBB0_618
	s_mov_b64 s[14:15], exec
	v_mbcnt_lo_u32_b32 v0, s14, 0
	v_mbcnt_hi_u32_b32 v0, s15, v0
	v_cmp_eq_u32_e32 vcc, 0, v0
	s_waitcnt vmcnt(0) expcnt(0) lgkmcnt(0)
	s_and_saveexec_b64 s[12:13], vcc
	s_cbranch_execz .LBB0_617
	v_readlane_b32 s4, v254, 6
	s_lshl_b32 s4, s4, 6
	s_add_u32 s4, s0, s4
	s_addc_u32 s5, s1, 0
	s_bcnt1_i32_b64 s14, s[14:15]
	v_mov_b32_e32 v1, 0x6000
	v_mov_b32_e32 v2, s14
	global_atomic_add v1, v1, v2, s[4:5] offset:1024 sc0
	buffer_inv sc1
.LBB0_617:
	s_or_b64 exec, exec, s[12:13]
	s_waitcnt vmcnt(1)
	v_readfirstlane_b32 s4, v1
	s_nop 1
	v_add_u32_e32 v2, s4, v0

.LBB0_633:
	s_or_b64 exec, exec, s[10:11]
	s_waitcnt vmcnt(0) lgkmcnt(0)
	s_waitcnt vmcnt(0)

.LBB0_739:
	s_and_b64 vcc, exec, s[12:13]
	s_cbranch_vccz .LBB0_761
	s_waitcnt vmcnt(0)
	v_mov_b32_e32 v2, 0
	s_waitcnt lgkmcnt(0)
	s_barrier
	s_mov_b64 s[12:13], exec
	v_readlane_b32 s4, v254, 2
	v_readlane_b32 s5, v254, 3
	s_and_b64 s[4:5], s[12:13], s[4:5]
	s_mov_b64 exec, s[4:5]
	s_cbranch_execz .LBB0_744
	s_mov_b64 s[20:21], exec
	v_mbcnt_lo_u32_b32 v0, s20, 0
	v_mbcnt_hi_u32_b32 v0, s21, v0
	v_cmp_eq_u32_e32 vcc, 0, v0
	s_waitcnt vmcnt(0) expcnt(0) lgkmcnt(0)
	s_and_saveexec_b64 s[14:15], vcc
	s_cbranch_execz .LBB0_743
	v_readlane_b32 s4, v254, 6
	s_lshl_b32 s4, s4, 6
	s_add_u32 s4, s0, s4
	s_addc_u32 s5, s1, 0
	s_bcnt1_i32_b64 s20, s[20:21]
	v_mov_b32_e32 v1, 0x6000
	v_mov_b32_e32 v2, s20
	global_atomic_add v1, v1, v2, s[4:5] offset:1024 sc0
	buffer_inv sc1
.LBB0_743:
	s_or_b64 exec, exec, s[14:15]
	s_waitcnt vmcnt(1)
	v_readfirstlane_b32 s4, v1
	s_nop 1
	v_add_u32_e32 v2, s4, v0

.LBB0_759:
	s_or_b64 exec, exec, s[12:13]
	s_waitcnt vmcnt(0) lgkmcnt(0)
	s_waitcnt vmcnt(0)

.LBB0_870:
	s_and_b64 vcc, exec, s[6:7]
	s_cbranch_vccz .LBB0_890
	s_waitcnt vmcnt(0)
	s_waitcnt lgkmcnt(0)
	s_barrier
	s_mov_b64 s[6:7], exec
	v_readlane_b32 s4, v254, 2
	v_readlane_b32 s5, v254, 3
	s_and_b64 s[4:5], s[6:7], s[4:5]
	s_mov_b64 exec, s[4:5]
	s_cbranch_execz .LBB0_889
	s_mov_b32 s4, 0x20120
	s_addk_i32 s4, 0x100
	v_mov_b32_e32 v0, s4
	s_waitcnt vmcnt(0) expcnt(0) lgkmcnt(0)
	ds_read_b32 v0, v0
	s_mov_b64 s[10:11], exec
	v_readlane_b32 s4, v254, 1
	s_lshl_b32 s4, s4, 8
	v_mbcnt_lo_u32_b32 v1, s10, 0
	s_add_u32 s8, s0, s4
	v_mbcnt_hi_u32_b32 v1, s11, v1
	s_addc_u32 s9, s1, 0
	v_cmp_eq_u32_e32 vcc, 0, v1
	s_and_saveexec_b64 s[12:13], vcc
	s_cbranch_execz .LBB0_874
	s_bcnt1_i32_b64 s4, s[10:11]
	v_mov_b32_e32 v2, 0x3000
	v_mov_b32_e32 v3, s4
	global_atomic_add v2, v2, v3, s[8:9] offset:1792 sc0
	buffer_inv sc1
.LBB0_874:
	s_or_b64 exec, exec, s[12:13]
	s_waitcnt lgkmcnt(0)
	v_cvt_f32_u32_e32 v3, v0
	s_waitcnt vmcnt(1)
	v_readfirstlane_b32 s4, v2
	s_add_u32 s10, s8, 0x4700
	s_addc_u32 s11, s9, 0
	v_rcp_iflag_f32_e32 v3, v3
	v_add_u32_e32 v1, s4, v1
	v_add_u32_e32 v4, 1, v1
	s_mov_b64 s[12:13], -1
	v_mul_f32_e32 v2, 0x4f7ffffe, v3
	v_cvt_u32_f32_e32 v2, v2
	v_sub_u32_e32 v3, 0, v0
	v_mul_lo_u32 v3, v3, v2
	v_mul_hi_u32 v3, v2, v3
	v_add_u32_e32 v2, v2, v3
	v_mul_hi_u32 v2, v1, v2
	v_mul_lo_u32 v3, v2, v0
	v_sub_u32_e32 v1, v1, v3
	v_add_u32_e32 v5, 1, v2
	v_cmp_ge_u32_e32 vcc, v1, v0
	v_sub_u32_e32 v3, v1, v0
	s_nop 0
	v_cndmask_b32_e32 v2, v2, v5, vcc
	v_cndmask_b32_e32 v1, v1, v3, vcc
	v_add_u32_e32 v3, 1, v2
	v_cmp_ge_u32_e32 vcc, v1, v0
	s_nop 1
	v_cndmask_b32_e32 v2, v2, v3, vcc
	v_mul_lo_u32 v1, v0, v2
	v_add_u32_e32 v0, v1, v0
	v_cmp_ne_u32_e32 vcc, v4, v0
	v_mov_b64_e32 v[0:1], s[10:11]
	s_and_saveexec_b64 s[8:9], vcc
	s_cbranch_execz .LBB0_886
	v_mov_b32_e32 v0, 0
	global_load_dword v1, v0, s[10:11] sc1
	s_mov_b64 s[16:17], 0
	s_waitcnt vmcnt(0)
	v_cmp_eq_u32_e32 vcc, v1, v2
	s_and_saveexec_b64 s[14:15], vcc
	s_cbranch_execz .LBB0_885
	s_add_u32 s12, s46, 0x4200
	s_addc_u32 s13, s47, 0
	s_mov_b32 s4, 1
	s_branch .LBB0_878

.LBB0_888:
	s_or_b64 exec, exec, s[8:9]
	s_waitcnt vmcnt(0)
	s_waitcnt vmcnt(0)

.LBB0_1084:
	s_and_b64 vcc, exec, s[10:11]
	s_cbranch_vccz .LBB0_1106
	s_waitcnt vmcnt(0)
	v_mov_b32_e32 v0, 1
	s_waitcnt lgkmcnt(0)
	v_mov_b32_e32 v1, 0
	s_barrier
	s_mov_b64 s[10:11], exec
	v_readlane_b32 s4, v254, 2
	v_readlane_b32 s5, v254, 3
	s_and_b64 s[4:5], s[10:11], s[4:5]
	s_mov_b64 exec, s[4:5]
	s_cbranch_execz .LBB0_1089
	s_mov_b32 s4, 0x20120
	s_addk_i32 s4, 0x100
	v_mov_b32_e32 v0, s4
	s_waitcnt vmcnt(0) expcnt(0) lgkmcnt(0)
	ds_read_b32 v0, v0
	s_mov_b64 s[12:13], exec
	v_mbcnt_lo_u32_b32 v1, s12, 0
	v_mbcnt_hi_u32_b32 v1, s13, v1
	v_cmp_eq_u32_e32 vcc, 0, v1
	s_and_saveexec_b64 s[14:15], vcc
	s_cbranch_execz .LBB0_1088
	v_readlane_b32 s4, v254, 1
	s_lshl_b32 s4, s4, 8
	v_readlane_b32 s16, v254, 13
	v_readlane_b32 s17, v254, 14
	s_add_u32 s4, s16, s4
	s_addc_u32 s5, s17, 0
	s_bcnt1_i32_b64 s12, s[12:13]
	v_mov_b32_e32 v2, 0x3000
	v_mov_b32_e32 v3, s12
	global_atomic_add v2, v2, v3, s[4:5] offset:1792 sc0
	buffer_inv sc1
.LBB0_1088:
	s_or_b64 exec, exec, s[14:15]
	s_waitcnt vmcnt(1)
	v_readfirstlane_b32 s4, v2
	s_nop 1
	v_add_u32_e32 v1, s4, v1

.LBB0_1104:
	s_or_b64 exec, exec, s[10:11]
	s_waitcnt vmcnt(0)
	s_waitcnt vmcnt(0)

.LBB0_1209:
	s_and_b64 vcc, exec, s[14:15]
	s_cbranch_vccz .LBB0_1231
	s_waitcnt vmcnt(0)
	v_mov_b32_e32 v2, 0
	s_waitcnt lgkmcnt(0)
	s_barrier
	s_mov_b64 s[14:15], exec
	v_readlane_b32 s4, v254, 2
	v_readlane_b32 s5, v254, 3
	s_and_b64 s[4:5], s[14:15], s[4:5]
	s_mov_b64 exec, s[4:5]
	s_cbranch_execz .LBB0_1214
	s_mov_b64 s[18:19], exec
	v_mbcnt_lo_u32_b32 v0, s18, 0
	v_mbcnt_hi_u32_b32 v0, s19, v0
	v_cmp_eq_u32_e32 vcc, 0, v0
	s_waitcnt vmcnt(0) expcnt(0) lgkmcnt(0)
	s_and_saveexec_b64 s[16:17], vcc
	s_cbranch_execz .LBB0_1213
	v_readlane_b32 s4, v254, 6
	s_lshl_b32 s4, s4, 6
	v_readlane_b32 s20, v254, 13
	v_readlane_b32 s21, v254, 14
	s_add_u32 s4, s20, s4
	s_addc_u32 s5, s21, 0
	s_bcnt1_i32_b64 s18, s[18:19]
	v_mov_b32_e32 v1, 0x6000
	v_mov_b32_e32 v2, s18
	global_atomic_add v1, v1, v2, s[4:5] offset:1024 sc0
	buffer_inv sc1
.LBB0_1213:
	s_or_b64 exec, exec, s[16:17]
	s_waitcnt vmcnt(1)
	v_readfirstlane_b32 s4, v1
	s_nop 1
	v_add_u32_e32 v2, s4, v0

.LBB0_1229:
	s_or_b64 exec, exec, s[14:15]
	s_waitcnt vmcnt(0) lgkmcnt(0)
	s_waitcnt vmcnt(0)

.LBB0_1324:
	s_and_b64 vcc, exec, s[12:13]
	s_cbranch_vccz .LBB0_1346
	s_waitcnt vmcnt(0)
	v_mov_b32_e32 v2, 0
	s_waitcnt lgkmcnt(0)
	s_barrier
	s_mov_b64 s[12:13], exec
	v_readlane_b32 s4, v254, 2
	v_readlane_b32 s5, v254, 3
	s_and_b64 s[4:5], s[12:13], s[4:5]
	s_mov_b64 exec, s[4:5]
	s_cbranch_execz .LBB0_1329
	s_mov_b64 s[16:17], exec
	v_mbcnt_lo_u32_b32 v0, s16, 0
	v_mbcnt_hi_u32_b32 v0, s17, v0
	v_cmp_eq_u32_e32 vcc, 0, v0
	s_waitcnt vmcnt(0) expcnt(0) lgkmcnt(0)
	s_and_saveexec_b64 s[14:15], vcc
	s_cbranch_execz .LBB0_1328
	v_readlane_b32 s4, v254, 6
	s_lshl_b32 s4, s4, 6
	v_readlane_b32 s18, v254, 13
	v_readlane_b32 s19, v254, 14
	s_add_u32 s4, s18, s4
	s_addc_u32 s5, s19, 0
	s_bcnt1_i32_b64 s16, s[16:17]
	v_mov_b32_e32 v1, 0x6000
	v_mov_b32_e32 v2, s16
	global_atomic_add v1, v1, v2, s[4:5] offset:1024 sc0
	buffer_inv sc1

.LBB0_1344:
	s_or_b64 exec, exec, s[4:5]
	s_waitcnt vmcnt(0) lgkmcnt(0)
	s_waitcnt vmcnt(0)

.LBB0_1376:
	v_lshl_add_u32 v112, s53, 8, v172
	v_ashrrev_i32_e32 v113, 31, v112
	v_lshl_or_b32 v114, s54, 8, v173
	v_lshlrev_b64 v[132:133], 11, v[112:113]
	v_lshl_add_u64 v[132:133], s[64:65], 0, v[132:133]
	v_ashrrev_i32_e32 v115, 31, v114
	v_lshl_add_u64 v[132:133], v[114:115], 1, v[132:133]
	v_add_co_u32_e32 v134, vcc, 0x8000, v132
	global_load_dwordx4 v[180:183], v[132:133], off
	global_load_dwordx4 v[184:187], v[132:133], off offset:256
	v_addc_co_u32_e32 v135, vcc, 0, v133, vcc
	global_load_dwordx4 v[188:191], v[134:135], off
	global_load_dwordx4 v[192:195], v[134:135], off offset:256
	v_lshlrev_b64 v[112:113], 12, v[112:113]
	v_lshl_add_u64 v[112:113], s[44:45], 0, v[112:113]
	v_lshl_add_u64 v[166:167], v[114:115], 2, v[112:113]
	v_add_co_u32_e32 v112, vcc, 0x10000, v132
	s_nop 0
	s_nop 0
	v_addc_co_u32_e32 v113, vcc, 0, v133, vcc
	global_load_dwordx4 v[196:199], v[112:113], off
	global_load_dwordx4 v[200:203], v[112:113], off offset:256
	v_add_co_u32_e32 v114, vcc, s26, v132
	s_nop 0
	s_nop 0
	v_addc_co_u32_e32 v115, vcc, 0, v133, vcc
	global_load_dwordx4 v[204:207], v[114:115], off
	global_load_dwordx4 v[160:163], v[114:115], off offset:256
	v_add_co_u32_e32 v112, vcc, 0x40000, v132
	s_nop 0
	s_nop 0
	v_addc_co_u32_e32 v113, vcc, 0, v133, vcc
	global_load_dwordx4 v[156:159], v[112:113], off
	global_load_dwordx4 v[152:155], v[112:113], off offset:256
	v_add_co_u32_e32 v114, vcc, 0x48000, v132
	s_nop 0
	s_nop 0
	v_addc_co_u32_e32 v115, vcc, 0, v133, vcc
	global_load_dwordx4 v[148:151], v[114:115], off
	global_load_dwordx4 v[144:147], v[114:115], off offset:256
	v_add_co_u32_e32 v112, vcc, 0x50000, v132
	s_nop 0
	s_nop 0
	v_addc_co_u32_e32 v113, vcc, 0, v133, vcc
	global_load_dwordx4 v[140:143], v[112:113], off
	global_load_dwordx4 v[136:139], v[112:113], off offset:256
	v_add_co_u32_e32 v114, vcc, 0x58000, v132
	s_nop 0
	s_nop 0
	v_addc_co_u32_e32 v115, vcc, 0, v133, vcc
	global_load_dwordx4 v[132:135], v[114:115], off
	s_nop 0
	global_load_dwordx4 v[112:115], v[114:115], off offset:256
	s_waitcnt vmcnt(15)
	v_lshlrev_b32_e32 v208, 16, v180
	v_and_b32_e32 v209, 0xffff0000, v180
	v_lshlrev_b32_e32 v180, 16, v181
	v_and_b32_e32 v181, 0xffff0000, v181
	v_lshlrev_b32_e32 v210, 16, v182
	v_and_b32_e32 v211, 0xffff0000, v182
	v_lshlrev_b32_e32 v182, 16, v183
	v_and_b32_e32 v183, 0xffff0000, v183
	s_waitcnt vmcnt(14)
	v_lshlrev_b32_e32 v212, 16, v184
	v_and_b32_e32 v213, 0xffff0000, v184
	v_lshlrev_b32_e32 v184, 16, v185
	v_and_b32_e32 v185, 0xffff0000, v185
	v_lshlrev_b32_e32 v214, 16, v186
	v_and_b32_e32 v215, 0xffff0000, v186
	v_lshlrev_b32_e32 v186, 16, v187
	v_and_b32_e32 v187, 0xffff0000, v187
	v_pk_fma_f32 v[122:123], v[122:123], 0.5, v[180:181] op_sel_hi:[1,0,1]
	v_pk_fma_f32 v[120:121], v[120:121], 0.5, v[208:209] op_sel_hi:[1,0,1]
	v_pk_fma_f32 v[116:117], v[116:117], 0.5, v[210:211] op_sel_hi:[1,0,1]
	v_pk_fma_f32 v[118:119], v[118:119], 0.5, v[182:183] op_sel_hi:[1,0,1]
	v_pk_fma_f32 v[130:131], v[130:131], 0.5, v[184:185] op_sel_hi:[1,0,1]
	v_pk_fma_f32 v[128:129], v[128:129], 0.5, v[212:213] op_sel_hi:[1,0,1]
	v_pk_fma_f32 v[126:127], v[126:127], 0.5, v[186:187] op_sel_hi:[1,0,1]
	v_pk_fma_f32 v[124:125], v[124:125], 0.5, v[214:215] op_sel_hi:[1,0,1]
	global_store_dwordx4 v[166:167], v[120:123], off nt
	global_store_dwordx4 v[166:167], v[116:119], off offset:16 nt
	global_store_dwordx4 v[166:167], v[128:131], off offset:512 nt
	global_store_dwordx4 v[166:167], v[124:127], off offset:528 nt
	s_waitcnt vmcnt(17)
	v_lshlrev_b32_e32 v116, 16, v188
	v_and_b32_e32 v117, 0xffff0000, v188
	v_lshlrev_b32_e32 v118, 16, v189
	v_and_b32_e32 v119, 0xffff0000, v189
	v_lshlrev_b32_e32 v120, 16, v190
	v_and_b32_e32 v121, 0xffff0000, v190
	v_lshlrev_b32_e32 v122, 16, v191
	v_and_b32_e32 v123, 0xffff0000, v191
	v_pk_fma_f32 v[108:109], v[108:109], 0.5, v[116:117] op_sel_hi:[1,0,1]
	v_add_co_u32_e32 v116, vcc, s35, v166
	v_pk_fma_f32 v[110:111], v[110:111], 0.5, v[118:119] op_sel_hi:[1,0,1]
	v_pk_fma_f32 v[106:107], v[106:107], 0.5, v[122:123] op_sel_hi:[1,0,1]
	v_pk_fma_f32 v[104:105], v[104:105], 0.5, v[120:121] op_sel_hi:[1,0,1]
	v_addc_co_u32_e32 v117, vcc, 0, v167, vcc
	global_store_dwordx4 v[116:117], v[108:111], off nt
	global_store_dwordx4 v[116:117], v[104:107], off offset:16 nt
	s_waitcnt vmcnt(18)
	v_lshlrev_b32_e32 v108, 16, v194
	v_lshlrev_b32_e32 v104, 16, v192
	v_and_b32_e32 v105, 0xffff0000, v192
	v_lshlrev_b32_e32 v106, 16, v193
	v_and_b32_e32 v107, 0xffff0000, v193
	v_and_b32_e32 v109, 0xffff0000, v194
	v_lshlrev_b32_e32 v110, 16, v195
	v_and_b32_e32 v111, 0xffff0000, v195
	v_pk_fma_f32 v[102:103], v[102:103], 0.5, v[106:107] op_sel_hi:[1,0,1]
	v_pk_fma_f32 v[100:101], v[100:101], 0.5, v[104:105] op_sel_hi:[1,0,1]
	v_pk_fma_f32 v[96:97], v[96:97], 0.5, v[108:109] op_sel_hi:[1,0,1]
	v_pk_fma_f32 v[98:99], v[98:99], 0.5, v[110:111] op_sel_hi:[1,0,1]
	global_store_dwordx4 v[116:117], v[100:103], off offset:512 nt
	global_store_dwordx4 v[116:117], v[96:99], off offset:528 nt
	s_waitcnt vmcnt(19)
	v_lshlrev_b32_e32 v100, 16, v198
	v_lshlrev_b32_e32 v96, 16, v196
	v_and_b32_e32 v97, 0xffff0000, v196
	v_lshlrev_b32_e32 v98, 16, v197
	v_and_b32_e32 v99, 0xffff0000, v197
	v_and_b32_e32 v101, 0xffff0000, v198
	v_lshlrev_b32_e32 v102, 16, v199
	v_and_b32_e32 v103, 0xffff0000, v199
	v_pk_fma_f32 v[92:93], v[92:93], 0.5, v[96:97] op_sel_hi:[1,0,1]
	v_add_co_u32_e32 v96, vcc, s42, v166
	v_pk_fma_f32 v[94:95], v[94:95], 0.5, v[98:99] op_sel_hi:[1,0,1]
	v_pk_fma_f32 v[90:91], v[90:91], 0.5, v[102:103] op_sel_hi:[1,0,1]
	v_pk_fma_f32 v[88:89], v[88:89], 0.5, v[100:101] op_sel_hi:[1,0,1]
	v_addc_co_u32_e32 v97, vcc, 0, v167, vcc
	global_store_dwordx4 v[96:97], v[92:95], off nt
	global_store_dwordx4 v[96:97], v[88:91], off offset:16 nt
	s_waitcnt vmcnt(20)
	v_lshlrev_b32_e32 v92, 16, v202
	v_lshlrev_b32_e32 v88, 16, v200
	v_and_b32_e32 v89, 0xffff0000, v200
	v_lshlrev_b32_e32 v90, 16, v201
	v_and_b32_e32 v91, 0xffff0000, v201
	v_and_b32_e32 v93, 0xffff0000, v202
	v_lshlrev_b32_e32 v94, 16, v203
	v_and_b32_e32 v95, 0xffff0000, v203
	v_pk_fma_f32 v[86:87], v[86:87], 0.5, v[90:91] op_sel_hi:[1,0,1]
	v_pk_fma_f32 v[84:85], v[84:85], 0.5, v[88:89] op_sel_hi:[1,0,1]
	v_pk_fma_f32 v[80:81], v[80:81], 0.5, v[92:93] op_sel_hi:[1,0,1]
	v_pk_fma_f32 v[82:83], v[82:83], 0.5, v[94:95] op_sel_hi:[1,0,1]
	global_store_dwordx4 v[96:97], v[84:87], off offset:512 nt
	global_store_dwordx4 v[96:97], v[80:83], off offset:528 nt
	s_waitcnt vmcnt(21)
	v_lshlrev_b32_e32 v84, 16, v206
	v_lshlrev_b32_e32 v80, 16, v204
	v_and_b32_e32 v81, 0xffff0000, v204
	v_lshlrev_b32_e32 v82, 16, v205
	v_and_b32_e32 v83, 0xffff0000, v205
	v_and_b32_e32 v85, 0xffff0000, v206
	v_lshlrev_b32_e32 v86, 16, v207
	v_and_b32_e32 v87, 0xffff0000, v207
	v_pk_fma_f32 v[76:77], v[76:77], 0.5, v[80:81] op_sel_hi:[1,0,1]
	v_add_co_u32_e32 v80, vcc, s43, v166
	v_pk_fma_f32 v[78:79], v[78:79], 0.5, v[82:83] op_sel_hi:[1,0,1]
	v_pk_fma_f32 v[74:75], v[74:75], 0.5, v[86:87] op_sel_hi:[1,0,1]
	v_pk_fma_f32 v[72:73], v[72:73], 0.5, v[84:85] op_sel_hi:[1,0,1]
	v_addc_co_u32_e32 v81, vcc, 0, v167, vcc
	global_store_dwordx4 v[80:81], v[76:79], off nt
	global_store_dwordx4 v[80:81], v[72:75], off offset:16 nt
	s_waitcnt vmcnt(22)
	v_lshlrev_b32_e32 v76, 16, v162
	v_lshlrev_b32_e32 v72, 16, v160
	v_and_b32_e32 v73, 0xffff0000, v160
	v_lshlrev_b32_e32 v74, 16, v161
	v_and_b32_e32 v75, 0xffff0000, v161
	v_and_b32_e32 v77, 0xffff0000, v162
	v_lshlrev_b32_e32 v78, 16, v163
	v_and_b32_e32 v79, 0xffff0000, v163
	v_pk_fma_f32 v[62:63], v[62:63], 0.5, v[74:75] op_sel_hi:[1,0,1]
	v_pk_fma_f32 v[60:61], v[60:61], 0.5, v[72:73] op_sel_hi:[1,0,1]
	v_pk_fma_f32 v[58:59], v[58:59], 0.5, v[78:79] op_sel_hi:[1,0,1]
	v_pk_fma_f32 v[56:57], v[56:57], 0.5, v[76:77] op_sel_hi:[1,0,1]
	global_store_dwordx4 v[80:81], v[60:63], off offset:512 nt
	global_store_dwordx4 v[80:81], v[56:59], off offset:528 nt
	s_waitcnt vmcnt(23)
	v_lshlrev_b32_e32 v60, 16, v158
	v_and_b32_e32 v61, 0xffff0000, v158
	v_lshlrev_b32_e32 v56, 16, v156
	v_and_b32_e32 v57, 0xffff0000, v156
	v_lshlrev_b32_e32 v58, 16, v157
	v_and_b32_e32 v59, 0xffff0000, v157
	v_pk_fma_f32 v[60:61], v[64:65], 0.5, v[60:61] op_sel_hi:[1,0,1]
	v_add_co_u32_e32 v64, vcc, s46, v166
	v_lshlrev_b32_e32 v62, 16, v159
	v_and_b32_e32 v63, 0xffff0000, v159
	v_pk_fma_f32 v[58:59], v[70:71], 0.5, v[58:59] op_sel_hi:[1,0,1]
	v_pk_fma_f32 v[56:57], v[68:69], 0.5, v[56:57] op_sel_hi:[1,0,1]
	v_addc_co_u32_e32 v65, vcc, 0, v167, vcc
	v_pk_fma_f32 v[62:63], v[66:67], 0.5, v[62:63] op_sel_hi:[1,0,1]
	global_store_dwordx4 v[64:65], v[56:59], off nt
	global_store_dwordx4 v[64:65], v[60:63], off offset:16 nt
	s_waitcnt vmcnt(24)
	v_lshlrev_b32_e32 v56, 16, v152
	v_and_b32_e32 v57, 0xffff0000, v152
	v_lshlrev_b32_e32 v58, 16, v153
	v_and_b32_e32 v59, 0xffff0000, v153
	v_lshlrev_b32_e32 v60, 16, v154
	v_and_b32_e32 v61, 0xffff0000, v154
	v_lshlrev_b32_e32 v62, 16, v155
	v_and_b32_e32 v63, 0xffff0000, v155
	v_pk_fma_f32 v[54:55], v[54:55], 0.5, v[58:59] op_sel_hi:[1,0,1]
	v_pk_fma_f32 v[52:53], v[52:53], 0.5, v[56:57] op_sel_hi:[1,0,1]
	v_pk_fma_f32 v[48:49], v[48:49], 0.5, v[60:61] op_sel_hi:[1,0,1]
	v_pk_fma_f32 v[50:51], v[50:51], 0.5, v[62:63] op_sel_hi:[1,0,1]
	global_store_dwordx4 v[64:65], v[52:55], off offset:512 nt
	global_store_dwordx4 v[64:65], v[48:51], off offset:528 nt
	s_waitcnt vmcnt(25)
	v_lshlrev_b32_e32 v52, 16, v150
	v_lshlrev_b32_e32 v48, 16, v148
	v_and_b32_e32 v49, 0xffff0000, v148
	v_lshlrev_b32_e32 v50, 16, v149
	v_and_b32_e32 v51, 0xffff0000, v149
	v_and_b32_e32 v53, 0xffff0000, v150
	v_lshlrev_b32_e32 v54, 16, v151
	v_and_b32_e32 v55, 0xffff0000, v151
	v_pk_fma_f32 v[44:45], v[44:45], 0.5, v[48:49] op_sel_hi:[1,0,1]
	v_add_co_u32_e32 v48, vcc, s47, v166
	v_pk_fma_f32 v[46:47], v[46:47], 0.5, v[50:51] op_sel_hi:[1,0,1]
	v_pk_fma_f32 v[42:43], v[42:43], 0.5, v[54:55] op_sel_hi:[1,0,1]
	v_pk_fma_f32 v[40:41], v[40:41], 0.5, v[52:53] op_sel_hi:[1,0,1]
	v_addc_co_u32_e32 v49, vcc, 0, v167, vcc
	global_store_dwordx4 v[48:49], v[44:47], off nt
	global_store_dwordx4 v[48:49], v[40:43], off offset:16 nt
	s_waitcnt vmcnt(26)
	v_lshlrev_b32_e32 v44, 16, v146
	v_lshlrev_b32_e32 v40, 16, v144
	v_and_b32_e32 v41, 0xffff0000, v144
	v_lshlrev_b32_e32 v42, 16, v145
	v_and_b32_e32 v43, 0xffff0000, v145
	v_and_b32_e32 v45, 0xffff0000, v146
	v_lshlrev_b32_e32 v46, 16, v147
	v_and_b32_e32 v47, 0xffff0000, v147
	v_pk_fma_f32 v[38:39], v[38:39], 0.5, v[42:43] op_sel_hi:[1,0,1]
	v_pk_fma_f32 v[36:37], v[36:37], 0.5, v[40:41] op_sel_hi:[1,0,1]
	v_pk_fma_f32 v[32:33], v[32:33], 0.5, v[44:45] op_sel_hi:[1,0,1]
	v_pk_fma_f32 v[34:35], v[34:35], 0.5, v[46:47] op_sel_hi:[1,0,1]
	global_store_dwordx4 v[48:49], v[36:39], off offset:512 nt
	global_store_dwordx4 v[48:49], v[32:35], off offset:528 nt
	s_waitcnt vmcnt(27)
	v_lshlrev_b32_e32 v36, 16, v142
	v_lshlrev_b32_e32 v32, 16, v140
	v_and_b32_e32 v33, 0xffff0000, v140
	v_lshlrev_b32_e32 v34, 16, v141
	v_and_b32_e32 v35, 0xffff0000, v141
	v_and_b32_e32 v37, 0xffff0000, v142
	v_lshlrev_b32_e32 v38, 16, v143
	v_and_b32_e32 v39, 0xffff0000, v143
	v_pk_fma_f32 v[28:29], v[28:29], 0.5, v[32:33] op_sel_hi:[1,0,1]
	v_add_co_u32_e32 v32, vcc, s48, v166
	v_pk_fma_f32 v[30:31], v[30:31], 0.5, v[34:35] op_sel_hi:[1,0,1]
	v_pk_fma_f32 v[26:27], v[26:27], 0.5, v[38:39] op_sel_hi:[1,0,1]
	v_pk_fma_f32 v[24:25], v[24:25], 0.5, v[36:37] op_sel_hi:[1,0,1]
	v_addc_co_u32_e32 v33, vcc, 0, v167, vcc
	global_store_dwordx4 v[32:33], v[28:31], off nt
	global_store_dwordx4 v[32:33], v[24:27], off offset:16 nt
	s_waitcnt vmcnt(28)
	v_lshlrev_b32_e32 v28, 16, v138
	v_lshlrev_b32_e32 v24, 16, v136
	v_and_b32_e32 v25, 0xffff0000, v136
	v_lshlrev_b32_e32 v26, 16, v137
	v_and_b32_e32 v27, 0xffff0000, v137
	v_and_b32_e32 v29, 0xffff0000, v138
	v_lshlrev_b32_e32 v30, 16, v139
	v_and_b32_e32 v31, 0xffff0000, v139
	v_pk_fma_f32 v[22:23], v[22:23], 0.5, v[26:27] op_sel_hi:[1,0,1]
	v_pk_fma_f32 v[20:21], v[20:21], 0.5, v[24:25] op_sel_hi:[1,0,1]
	v_pk_fma_f32 v[16:17], v[16:17], 0.5, v[28:29] op_sel_hi:[1,0,1]
	v_pk_fma_f32 v[18:19], v[18:19], 0.5, v[30:31] op_sel_hi:[1,0,1]
	global_store_dwordx4 v[32:33], v[20:23], off offset:512 nt
	global_store_dwordx4 v[32:33], v[16:19], off offset:528 nt
	s_waitcnt vmcnt(29)
	v_lshlrev_b32_e32 v20, 16, v134
	v_lshlrev_b32_e32 v16, 16, v132
	v_and_b32_e32 v17, 0xffff0000, v132
	v_lshlrev_b32_e32 v18, 16, v133
	v_and_b32_e32 v19, 0xffff0000, v133
	v_and_b32_e32 v21, 0xffff0000, v134
	v_lshlrev_b32_e32 v22, 16, v135
	v_and_b32_e32 v23, 0xffff0000, v135
	v_pk_fma_f32 v[12:13], v[12:13], 0.5, v[16:17] op_sel_hi:[1,0,1]
	v_add_co_u32_e32 v16, vcc, s49, v166
	v_pk_fma_f32 v[14:15], v[14:15], 0.5, v[18:19] op_sel_hi:[1,0,1]
	v_pk_fma_f32 v[10:11], v[10:11], 0.5, v[22:23] op_sel_hi:[1,0,1]
	v_pk_fma_f32 v[8:9], v[8:9], 0.5, v[20:21] op_sel_hi:[1,0,1]
	v_addc_co_u32_e32 v17, vcc, 0, v167, vcc
	global_store_dwordx4 v[16:17], v[12:15], off nt
	global_store_dwordx4 v[16:17], v[8:11], off offset:16 nt
	s_and_b64 vcc, exec, s[0:1]
	s_waitcnt vmcnt(30)
	v_lshlrev_b32_e32 v12, 16, v114
	v_lshlrev_b32_e32 v8, 16, v112
	v_and_b32_e32 v9, 0xffff0000, v112
	v_lshlrev_b32_e32 v10, 16, v113
	v_and_b32_e32 v11, 0xffff0000, v113
	v_and_b32_e32 v13, 0xffff0000, v114
	v_lshlrev_b32_e32 v14, 16, v115
	v_and_b32_e32 v15, 0xffff0000, v115
	v_pk_fma_f32 v[6:7], v[6:7], 0.5, v[10:11] op_sel_hi:[1,0,1]
	v_pk_fma_f32 v[4:5], v[4:5], 0.5, v[8:9] op_sel_hi:[1,0,1]
	s_mov_b64 s[0:1], -1
	v_pk_fma_f32 v[2:3], v[2:3], 0.5, v[14:15] op_sel_hi:[1,0,1]
	v_pk_fma_f32 v[0:1], v[0:1], 0.5, v[12:13] op_sel_hi:[1,0,1]
	global_store_dwordx4 v[16:17], v[4:7], off offset:512 nt
	global_store_dwordx4 v[16:17], v[0:3], off offset:528 nt
	s_cbranch_vccnz .LBB0_1360
	s_andn2_b64 vcc, exec, s[4:5]
	s_cbranch_vccnz .LBB0_1359
	s_barrier
	s_branch .LBB0_1359
